# dn_prep: second gate-column load of wave 0 issued right behind the first (was a second exposed global round trip per item); plus census/streamed-sample/leader-hoist bundle
# speedup vs baseline: 1.0100x; 1.0055x over previous
; __device__ __forceinline__ float silu_(float x) { return x * __builtin_amdgcn_rcpf(1.f + __expf(-x)); }
; __device__ __forceinline__ void phase_dn_prep(const KP kp, const int bid, const int G, int j, LAS unsigned char* lds, int tid0) {
;     ...
;         {
;           const int t0 = 8 * wave; const bool first = (n == 0 && wave == 0);
;           float qa[8], qb[8], ka[8], kb[8];
; #pragma unroll
;           for (int part = 0; part < 3; ++part) { const int c = part * 1024 + h * 128 + 2 * lane;
;               const float w0a = cw[c], w0b = cw[c + 1], w1a = cw[3072 + c], w1b = cw[3072 + c + 1], w2a = cw[2 * 3072 + c], w2b = cw[2 * 3072 + c + 1], w3a = cw[3 * 3072 + c], w3b = cw[3 * 3072 + c + 1];
;               unsigned raw[11];
; #pragma unroll
;               for (int q = 0; q < 11; ++q) raw[q] = rawq[part][q];
;               if (first) { raw[0] = 0u; raw[1] = 0u; raw[2] = 0u; }
; #pragma unroll
;               for (int t = 0; t < 8; ++t) {
;                   const float ya = silu_(w0a * __uint_as_float(raw[t] << 16) + w1a * __uint_as_float(raw[t + 1] << 16) + w2a * __uint_as_float(raw[t + 2] << 16) + w3a * __uint_as_float(raw[t + 3] << 16));
;                   const float yb = silu_(w0b * __uint_as_float(raw[t] & 0xffff0000u) + w1b * __uint_as_float(raw[t + 1] & 0xffff0000u) + w2b * __uint_as_float(raw[t + 2] & 0xffff0000u) + w3b * __uint_as_float(raw[t + 3] & 0xffff0000u));
;                   if (part == 0) { qa[t] = ya; qb[t] = yb; } else if (part == 1) { ka[t] = ya; kb[t] = yb; } else { XL[(t0 + t) * 257 + 2 * lane] = ya; XL[(t0 + t) * 257 + 2 * lane + 1] = yb; } } }
.LBB0_554:
	s_bfe_u32 s3, s8, 0x50003
	s_and_b32 s2, s8, 7
	v_mov_b32_e32 v20, v183
	s_cmp_eq_u32 s3, 0
	s_cselect_b64 s[0:1], -1, 0
	s_waitcnt vmcnt(0)
	v_and_b32_e32 v68, 63, v20
	v_cmp_gt_u32_e32 vcc, 64, v20
	s_and_b64 s[0:1], s[0:1], vcc
	v_lshlrev_b32_e32 v2, 3, v68
	v_ashrrev_i32_e32 v72, 6, v20
	v_lshl_or_b32 v0, s2, 9, v2
	v_cndmask_b32_e64 v34, v40, 0, s[0:1]
	v_cndmask_b32_e64 v35, v39, 0, s[0:1]
	v_cndmask_b32_e64 v36, v19, 0, s[0:1]
	v_cndmask_b32_e64 v21, v51, 0, s[0:1]
	v_cndmask_b32_e64 v28, v50, 0, s[0:1]
	v_cndmask_b32_e64 v29, v49, 0, s[0:1]
	v_cndmask_b32_e64 v25, v62, 0, s[0:1]
	v_cndmask_b32_e64 v23, v61, 0, s[0:1]
	v_cndmask_b32_e64 v31, v60, 0, s[0:1]
	s_movk_i32 s0, 0x2020
	v_lshl_add_u64 v[16:17], s[46:47], 0, v[0:1]
	v_mul_lo_u32 v3, v72, s0
	s_movk_i32 s0, 0x3000
	v_add_co_u32_e64 v4, s[42:43], s0, v16
	s_movk_i32 s0, 0x6000
	s_nop 0
	v_addc_co_u32_e64 v5, s[42:43], 0, v17, s[42:43]
	v_add_co_u32_e64 v6, s[42:43], s0, v16
	s_mov_b32 s0, 0x9000
	s_nop 0
	v_addc_co_u32_e64 v7, s[42:43], 0, v17, s[42:43]
	v_add_co_u32_e64 v10, s[42:43], s0, v16
	s_barrier
	v_add3_u32 v37, s58, v2, v3
	global_load_dwordx2 v[2:3], v[4:5], off offset:-4096
	global_load_dwordx2 v[8:9], v[6:7], off offset:-4096
	v_addc_co_u32_e64 v11, s[42:43], 0, v17, s[42:43]
	s_mov_b32 s0, 0xb000
	v_add_co_u32_e64 v14, s[42:43], s0, v16
	global_load_dwordx2 v[12:13], v[10:11], off offset:-4096
	s_nop 0
	v_addc_co_u32_e64 v15, s[42:43], 0, v17, s[42:43]
	global_load_dwordx2 v[14:15], v[14:15], off
	v_lshlrev_b32_e32 v22, 16, v23
	v_and_b32_e32 v23, 0xffff0000, v23
	v_lshlrev_b32_e32 v30, 16, v31
	v_and_b32_e32 v31, 0xffff0000, v31
	v_lshlrev_b32_e32 v24, 16, v25
	v_and_b32_e32 v25, 0xffff0000, v25
	v_lshlrev_b32_e32 v26, 16, v63
	v_and_b32_e32 v27, 0xffff0000, v63
	v_add_u32_e32 v73, 0x404, v37
	s_waitcnt vmcnt(2)
	v_pk_mul_f32 v[32:33], v[8:9], v[22:23]
	s_nop 0
	v_pk_fma_f32 v[30:31], v[2:3], v[30:31], v[32:33]
	s_waitcnt vmcnt(1)
	v_pk_fma_f32 v[30:31], v[12:13], v[24:25], v[30:31]
	s_waitcnt vmcnt(0)
	v_pk_fma_f32 v[30:31], v[14:15], v[26:27], v[30:31]
	s_nop 0
	v_mul_f32_e32 v32, 0xbfb8aa3b, v31
	v_exp_f32_e32 v32, v32
	s_nop 0
	v_add_f32_e32 v32, 1.0, v32
	v_rcp_f32_e32 v33, v32
	v_mul_f32_e32 v32, 0xbfb8aa3b, v30
	v_exp_f32_e32 v32, v32
	s_nop 0
	v_add_f32_e32 v32, 1.0, v32
	v_rcp_f32_e32 v32, v32
	s_nop 0
	v_pk_mul_f32 v[30:31], v[30:31], v[32:33]
	v_pk_mul_f32 v[32:33], v[8:9], v[24:25]
	ds_write_b64 v37, v[30:31]
	v_pk_fma_f32 v[22:23], v[2:3], v[22:23], v[32:33]
	v_lshlrev_b32_e32 v30, 16, v64
	v_and_b32_e32 v31, 0xffff0000, v64
	v_pk_fma_f32 v[22:23], v[12:13], v[26:27], v[22:23]
	s_nop 0
	v_pk_fma_f32 v[22:23], v[14:15], v[30:31], v[22:23]
	s_nop 0
	v_mul_f32_e32 v32, 0xbfb8aa3b, v23
	v_exp_f32_e32 v32, v32
	s_nop 0
	v_add_f32_e32 v32, 1.0, v32
	v_rcp_f32_e32 v33, v32
	v_mul_f32_e32 v32, 0xbfb8aa3b, v22
	v_exp_f32_e32 v32, v32
	s_nop 0
	v_add_f32_e32 v32, 1.0, v32
	v_rcp_f32_e32 v32, v32
	s_nop 0
	v_pk_mul_f32 v[22:23], v[22:23], v[32:33]
	v_pk_mul_f32 v[32:33], v[8:9], v[26:27]
	ds_write2_b32 v73, v22, v23 offset1:1
	v_pk_fma_f32 v[24:25], v[2:3], v[24:25], v[32:33]
	v_lshlrev_b32_e32 v22, 16, v65
	v_and_b32_e32 v23, 0xffff0000, v65
	v_pk_fma_f32 v[24:25], v[12:13], v[30:31], v[24:25]
	v_add_u32_e32 v73, 0xc0c, v37
	v_pk_fma_f32 v[24:25], v[14:15], v[22:23], v[24:25]
	s_nop 0
	v_mul_f32_e32 v32, 0xbfb8aa3b, v25
	v_exp_f32_e32 v32, v32
	s_nop 0
	v_add_f32_e32 v32, 1.0, v32
	v_rcp_f32_e32 v33, v32
	v_mul_f32_e32 v32, 0xbfb8aa3b, v24
	v_exp_f32_e32 v32, v32
	s_nop 0
	v_add_f32_e32 v32, 1.0, v32
	v_rcp_f32_e32 v32, v32
	s_nop 0
	v_pk_mul_f32 v[24:25], v[24:25], v[32:33]
	v_pk_mul_f32 v[32:33], v[8:9], v[30:31]
	ds_write_b64 v37, v[24:25] offset:2056
	v_pk_fma_f32 v[26:27], v[2:3], v[26:27], v[32:33]
	v_lshlrev_b32_e32 v24, 16, v66
	v_and_b32_e32 v25, 0xffff0000, v66
	v_pk_fma_f32 v[26:27], v[12:13], v[22:23], v[26:27]
	s_nop 0
	v_pk_fma_f32 v[26:27], v[14:15], v[24:25], v[26:27]
	s_nop 0
	v_mul_f32_e32 v32, 0xbfb8aa3b, v27
	v_exp_f32_e32 v32, v32
	s_nop 0
	v_add_f32_e32 v32, 1.0, v32
	v_rcp_f32_e32 v33, v32
	v_mul_f32_e32 v32, 0xbfb8aa3b, v26
	v_exp_f32_e32 v32, v32
	s_nop 0
	v_add_f32_e32 v32, 1.0, v32
	v_rcp_f32_e32 v32, v32
	s_nop 0
	v_pk_mul_f32 v[26:27], v[26:27], v[32:33]
	v_pk_mul_f32 v[32:33], v[8:9], v[22:23]
	ds_write2_b32 v73, v26, v27 offset1:1
	v_pk_fma_f32 v[30:31], v[2:3], v[30:31], v[32:33]
	v_lshlrev_b32_e32 v26, 16, v67
	v_and_b32_e32 v27, 0xffff0000, v67
	v_pk_fma_f32 v[30:31], v[12:13], v[24:25], v[30:31]
	v_add_u32_e32 v73, 0x1414, v37
	v_pk_fma_f32 v[30:31], v[14:15], v[26:27], v[30:31]
	s_nop 0
	v_mul_f32_e32 v32, 0xbfb8aa3b, v31
	v_exp_f32_e32 v32, v32
	s_nop 0
	v_add_f32_e32 v32, 1.0, v32
	v_rcp_f32_e32 v33, v32
	v_mul_f32_e32 v32, 0xbfb8aa3b, v30
	v_exp_f32_e32 v32, v32
	s_nop 0
	v_add_f32_e32 v32, 1.0, v32
	v_rcp_f32_e32 v32, v32
	s_nop 0
	v_pk_mul_f32 v[30:31], v[30:31], v[32:33]
	v_pk_mul_f32 v[32:33], v[8:9], v[24:25]
	ds_write_b64 v37, v[30:31] offset:4112
	v_pk_fma_f32 v[22:23], v[2:3], v[22:23], v[32:33]
	v_lshlrev_b32_e32 v30, 16, v69
	v_and_b32_e32 v31, 0xffff0000, v69
	v_pk_fma_f32 v[22:23], v[12:13], v[26:27], v[22:23]
	s_nop 0
	v_pk_fma_f32 v[22:23], v[14:15], v[30:31], v[22:23]
	s_nop 0
	v_mul_f32_e32 v32, 0xbfb8aa3b, v23
	v_exp_f32_e32 v32, v32
	s_nop 0
	v_add_f32_e32 v32, 1.0, v32
	v_rcp_f32_e32 v33, v32
	v_mul_f32_e32 v32, 0xbfb8aa3b, v22
	v_exp_f32_e32 v32, v32
	s_nop 0
	v_add_f32_e32 v32, 1.0, v32
	v_rcp_f32_e32 v32, v32
	s_nop 0
	v_pk_mul_f32 v[22:23], v[22:23], v[32:33]
	v_pk_mul_f32 v[32:33], v[8:9], v[26:27]
	ds_write2_b32 v73, v22, v23 offset1:1
	v_pk_fma_f32 v[24:25], v[2:3], v[24:25], v[32:33]
; #define LAS __attribute__((address_space(3)))
; __device__ __forceinline__ unsigned pk2(float lo, float hi) { return cvtpk(lo, hi); }
; __device__ __forceinline__ float silu_(float x) { return x * __builtin_amdgcn_rcpf(1.f + __expf(-x)); }
; __device__ __forceinline__ void phase_dn_prep(const KP kp, const int bid, const int G, int j, LAS unsigned char* lds, int tid0) {
;     ...
;           for (int part = 0; part < 3; ++part) { const int c = part * 1024 + h * 128 + 2 * lane;
;               const float w0a = cw[c], w0b = cw[c + 1], w1a = cw[3072 + c], w1b = cw[3072 + c + 1], w2a = cw[2 * 3072 + c], w2b = cw[2 * 3072 + c + 1], w3a = cw[3 * 3072 + c], w3b = cw[3 * 3072 + c + 1];
;               unsigned raw[11];
; #pragma unroll
;               for (int q = 0; q < 11; ++q) raw[q] = rawq[part][q];
;               if (first) { raw[0] = 0u; raw[1] = 0u; raw[2] = 0u; }
; #pragma unroll
;               for (int t = 0; t < 8; ++t) {
;                   const float ya = silu_(w0a * __uint_as_float(raw[t] << 16) + w1a * __uint_as_float(raw[t + 1] << 16) + w2a * __uint_as_float(raw[t + 2] << 16) + w3a * __uint_as_float(raw[t + 3] << 16));
;                   const float yb = silu_(w0b * __uint_as_float(raw[t] & 0xffff0000u) + w1b * __uint_as_float(raw[t + 1] & 0xffff0000u) + w2b * __uint_as_float(raw[t + 2] & 0xffff0000u) + w3b * __uint_as_float(raw[t + 3] & 0xffff0000u));
;                   if (part == 0) { qa[t] = ya; qb[t] = yb; } else if (part == 1) { ka[t] = ya; kb[t] = yb; } else { XL[(t0 + t) * 257 + 2 * lane] = ya; XL[(t0 + t) * 257 + 2 * lane + 1] = yb; } } }
; #pragma unroll
;           for (int t = 0; t < 8; ++t) { const float scq = rsqrtf(wave_sum(qa[t] * qa[t] + qb[t] * qb[t]) + 1e-6f) * 0.08838834764831845f, sck = rsqrtf(wave_sum(ka[t] * ka[t] + kb[t] * kb[t]) + 1e-6f);
;               *(LAS unsigned*)(Qb + (t0 + t) * 136 + 2 * lane) = pk2(qa[t] * scq, qb[t] * scq); *(LAS unsigned*)(Kb + (t0 + t) * 136 + 2 * lane) = pk2(ka[t] * sck, kb[t] * sck); } }
	v_lshlrev_b32_e32 v22, 16, v70
	v_and_b32_e32 v23, 0xffff0000, v70
	v_pk_fma_f32 v[24:25], v[12:13], v[30:31], v[24:25]
	v_pk_mul_f32 v[8:9], v[8:9], v[30:31]
	v_pk_fma_f32 v[24:25], v[14:15], v[22:23], v[24:25]
	v_pk_fma_f32 v[2:3], v[2:3], v[26:27], v[8:9]
	v_mul_f32_e32 v32, 0xbfb8aa3b, v25
	v_exp_f32_e32 v32, v32
	v_pk_fma_f32 v[2:3], v[12:13], v[22:23], v[2:3]
	v_lshlrev_b32_e32 v26, 16, v35
	v_and_b32_e32 v27, 0xffff0000, v35
	v_add_f32_e32 v32, 1.0, v32
	v_rcp_f32_e32 v33, v32
	v_mul_f32_e32 v32, 0xbfb8aa3b, v24
	v_exp_f32_e32 v32, v32
	v_lshlrev_b32_e32 v22, 16, v41
	v_and_b32_e32 v23, 0xffff0000, v41
	v_and_b32_e32 v35, 0xffff0000, v28
	v_add_f32_e32 v32, 1.0, v32
	v_rcp_f32_e32 v32, v32
	v_mov_b32_e32 v31, v1
	v_mov_b32_e32 v73, v1
	v_pk_mul_f32 v[24:25], v[24:25], v[32:33]
	ds_write_b64 v37, v[24:25] offset:6168
	v_lshlrev_b32_e32 v24, 16, v71
	v_and_b32_e32 v25, 0xffff0000, v71
	v_pk_fma_f32 v[2:3], v[14:15], v[24:25], v[2:3]
	v_add_u32_e32 v32, 0x1c1c, v37
	v_mul_f32_e32 v8, 0xbfb8aa3b, v3
	v_exp_f32_e32 v8, v8
	v_lshlrev_b32_e32 v24, 16, v34
	v_and_b32_e32 v25, 0xffff0000, v34
	v_lshlrev_b32_e32 v14, 2, v68
	v_add_f32_e32 v8, 1.0, v8
	v_rcp_f32_e32 v9, v8
	v_mul_f32_e32 v8, 0xbfb8aa3b, v2
	v_exp_f32_e32 v8, v8
	v_lshlrev_b32_e32 v34, 16, v28
	v_and_b32_e32 v33, 0xffff0000, v29
	v_and_b32_e32 v37, 0xffff0000, v21
	v_add_f32_e32 v8, 1.0, v8
	v_rcp_f32_e32 v8, v8
	s_nop 0
	v_pk_mul_f32 v[2:3], v[2:3], v[8:9]
	ds_write2_b32 v32, v2, v3 offset1:1
	global_load_dwordx2 v[2:3], v0, s[46:47]
	global_load_dwordx2 v[8:9], v[4:5], off
	s_nop 0
	global_load_dwordx2 v[4:5], v[6:7], off
	s_nop 0
	global_load_dwordx2 v[6:7], v[10:11], off
	v_lshlrev_b32_e32 v10, 16, v36
	v_and_b32_e32 v11, 0xffff0000, v36
	v_lshlrev_b32_e32 v32, 16, v29
	v_lshlrev_b32_e32 v36, 16, v21
	s_waitcnt vmcnt(2)
	v_pk_mul_f32 v[12:13], v[8:9], v[26:27]
	s_nop 0
	v_pk_fma_f32 v[10:11], v[2:3], v[10:11], v[12:13]
	s_waitcnt vmcnt(1)
	v_pk_fma_f32 v[10:11], v[4:5], v[24:25], v[10:11]
	s_waitcnt vmcnt(0)
	v_pk_fma_f32 v[10:11], v[6:7], v[22:23], v[10:11]
	s_nop 0
	v_mul_f32_e32 v0, 0xbfb8aa3b, v10
	v_exp_f32_e32 v0, v0
	s_nop 0
	v_add_f32_e32 v0, 1.0, v0
	v_rcp_f32_e32 v12, v0
	v_mul_f32_e32 v0, 0xbfb8aa3b, v11
	v_exp_f32_e32 v0, v0
	s_nop 0
	v_add_f32_e32 v0, 1.0, v0
	v_rcp_f32_e32 v13, v0
	s_nop 0
	v_pk_mul_f32 v[10:11], v[10:11], v[12:13]
	s_nop 0
	v_pk_mul_f32 v[12:13], v[10:11], v[10:11]
	s_nop 0
	v_add_f32_e32 v0, v12, v13
	v_mov_b32_e32 v12, v1
	s_nop 0
	v_add_f32_dpp v0, v0, v0 quad_perm:[1,0,3,2] row_mask:0xf bank_mask:0xf bound_ctrl:1
	s_nop 1
	v_add_f32_dpp v0, v0, v0 quad_perm:[2,3,0,1] row_mask:0xf bank_mask:0xf bound_ctrl:1
	s_nop 1
	v_add_f32_dpp v0, v0, v0 row_half_mirror row_mask:0xf bank_mask:0xf bound_ctrl:1
	s_nop 1
	v_add_f32_dpp v0, v0, v0 row_mirror row_mask:0xf bank_mask:0xf bound_ctrl:1
	s_nop 1
	v_mov_b32_dpp v12, v0 row_bcast:15 row_mask:0xa bank_mask:0xf
	v_add_f32_e32 v0, v0, v12
	v_mov_b32_e32 v12, v1
	s_nop 1
	v_mov_b32_dpp v12, v0 row_bcast:31 row_mask:0xc bank_mask:0xf
	v_add_f32_e32 v0, v0, v12
	s_nop 0
	v_readlane_b32 s0, v0, 63
	s_nop 1
	v_add_f32_e32 v0, s0, v214
	v_cmp_gt_f32_e64 s[42:43], s65, v0
	v_mul_f32_e32 v12, 0x4b800000, v0
	s_movk_i32 s0, 0x880
	v_cndmask_b32_e64 v0, v0, v12, s[42:43]
	v_rsq_f32_e32 v0, v0
	s_nop 0
	v_mul_f32_e32 v12, 0x45800000, v0
	v_cndmask_b32_e64 v0, v0, v12, s[42:43]
	v_mul_f32_e32 v0, 0x3db504f3, v0
	v_pk_mul_f32 v[10:11], v[10:11], v[0:1] op_sel_hi:[1,0]
	v_mul_lo_u32 v0, v72, s0
	s_movk_i32 s0, 0x1000
	v_cvt_pk_bf16_f32 v30, v10, v11
	v_add_co_u32_e64 v10, s[42:43], s0, v16
	s_movk_i32 s0, 0x7000
	s_nop 0
	v_addc_co_u32_e64 v11, s[42:43], 0, v17, s[42:43]
	v_add_co_u32_e64 v12, s[42:43], s88, v16
	v_add3_u32 v0, 0, v14, v0
	s_nop 0
	v_addc_co_u32_e64 v13, s[42:43], 0, v17, s[42:43]
	v_add_co_u32_e64 v14, s[42:43], s0, v16
	global_load_dwordx2 v[10:11], v[10:11], off
	s_nop 0
	v_addc_co_u32_e64 v15, s[42:43], 0, v17, s[42:43]
	global_load_dwordx2 v[12:13], v[12:13], off
	s_mov_b32 s0, 0xa000
	v_add_co_u32_e64 v16, s[42:43], s0, v16
	global_load_dwordx2 v[14:15], v[14:15], off
	s_nop 0
	v_addc_co_u32_e64 v17, s[42:43], 0, v17, s[42:43]
	global_load_dwordx2 v[16:17], v[16:17], off
	s_waitcnt vmcnt(2)
	v_pk_mul_f32 v[28:29], v[12:13], v[34:35]
	s_nop 0
	v_pk_fma_f32 v[28:29], v[10:11], v[32:33], v[28:29]
	v_lshlrev_b32_e32 v32, 16, v52
	v_and_b32_e32 v33, 0xffff0000, v52
	s_waitcnt vmcnt(1)
	v_pk_fma_f32 v[28:29], v[14:15], v[36:37], v[28:29]
	s_waitcnt vmcnt(0)
; #define LAS __attribute__((address_space(3)))
; __device__ __forceinline__ unsigned pk2(float lo, float hi) { return cvtpk(lo, hi); }
; __device__ __forceinline__ void phase_dn_prep(const KP kp, const int bid, const int G, int j, LAS unsigned char* lds, int tid0) {
;     ...
;           for (int t = 0; t < 8; ++t) { const float scq = rsqrtf(wave_sum(qa[t] * qa[t] + qb[t] * qb[t]) + 1e-6f) * 0.08838834764831845f, sck = rsqrtf(wave_sum(ka[t] * ka[t] + kb[t] * kb[t]) + 1e-6f);
;               *(LAS unsigned*)(Qb + (t0 + t) * 136 + 2 * lane) = pk2(qa[t] * scq, qb[t] * scq); *(LAS unsigned*)(Kb + (t0 + t) * 136 + 2 * lane) = pk2(ka[t] * sck, kb[t] * sck); } }
	v_pk_fma_f32 v[28:29], v[16:17], v[32:33], v[28:29]
	s_nop 0
	v_mul_f32_e32 v21, 0xbfb8aa3b, v28
	v_exp_f32_e32 v21, v21
	s_nop 0
	v_add_f32_e32 v21, 1.0, v21
	v_rcp_f32_e32 v74, v21
	v_mul_f32_e32 v21, 0xbfb8aa3b, v29
	v_exp_f32_e32 v21, v21
	s_nop 0
	v_add_f32_e32 v21, 1.0, v21
	v_rcp_f32_e32 v75, v21
	s_nop 0
	v_pk_mul_f32 v[28:29], v[28:29], v[74:75]
	s_nop 0
	v_pk_mul_f32 v[74:75], v[28:29], v[28:29]
	s_nop 0
	v_add_f32_e32 v21, v74, v75
	s_nop 1
	v_add_f32_dpp v21, v21, v21 quad_perm:[1,0,3,2] row_mask:0xf bank_mask:0xf bound_ctrl:1
	s_nop 1
	v_add_f32_dpp v21, v21, v21 quad_perm:[2,3,0,1] row_mask:0xf bank_mask:0xf bound_ctrl:1
	s_nop 1
	v_add_f32_dpp v21, v21, v21 row_half_mirror row_mask:0xf bank_mask:0xf bound_ctrl:1
	s_nop 1
	v_add_f32_dpp v21, v21, v21 row_mirror row_mask:0xf bank_mask:0xf bound_ctrl:1
	s_nop 1
	v_mov_b32_dpp v31, v21 row_bcast:15 row_mask:0xa bank_mask:0xf
	v_add_f32_e32 v21, v21, v31
	v_mov_b32_e32 v31, v1
	s_nop 1
	v_mov_b32_dpp v31, v21 row_bcast:31 row_mask:0xc bank_mask:0xf
	v_add_f32_e32 v21, v21, v31
	s_nop 0
	v_readlane_b32 s0, v21, 63
	s_nop 1
	v_add_f32_e32 v21, s0, v214
	v_cmp_gt_f32_e64 s[42:43], s65, v21
	v_mul_f32_e32 v31, 0x4b800000, v21
	s_nop 0
	v_cndmask_b32_e64 v21, v21, v31, s[42:43]
	v_rsq_f32_e32 v21, v21
	s_nop 0
	v_mul_f32_e32 v31, 0x45800000, v21
	v_cndmask_b32_e64 v74, v21, v31, s[42:43]
	v_pk_mul_f32 v[28:29], v[28:29], v[74:75] op_sel_hi:[1,0]
	v_pk_mul_f32 v[74:75], v[8:9], v[24:25]
	v_cvt_pk_bf16_f32 v21, v28, v29
	v_pk_fma_f32 v[26:27], v[2:3], v[26:27], v[74:75]
	v_lshlrev_b32_e32 v28, 16, v42
	v_and_b32_e32 v29, 0xffff0000, v42
	v_pk_fma_f32 v[26:27], v[4:5], v[22:23], v[26:27]
	s_nop 0
	v_pk_fma_f32 v[26:27], v[6:7], v[28:29], v[26:27]
	s_nop 0
	v_mul_f32_e32 v31, 0xbfb8aa3b, v26
	v_exp_f32_e32 v31, v31
	s_nop 0
	v_add_f32_e32 v31, 1.0, v31
	v_rcp_f32_e32 v74, v31
	v_mul_f32_e32 v31, 0xbfb8aa3b, v27
	v_exp_f32_e32 v31, v31
	s_nop 0
	v_add_f32_e32 v31, 1.0, v31
	v_rcp_f32_e32 v75, v31
	s_nop 0
	v_pk_mul_f32 v[26:27], v[26:27], v[74:75]
	s_nop 0
	v_pk_mul_f32 v[74:75], v[26:27], v[26:27]
	s_nop 0
	v_add_f32_e32 v31, v74, v75
	s_nop 1
	v_add_f32_dpp v31, v31, v31 quad_perm:[1,0,3,2] row_mask:0xf bank_mask:0xf bound_ctrl:1
	s_nop 1
	v_add_f32_dpp v31, v31, v31 quad_perm:[2,3,0,1] row_mask:0xf bank_mask:0xf bound_ctrl:1
	s_nop 1
	v_add_f32_dpp v31, v31, v31 row_half_mirror row_mask:0xf bank_mask:0xf bound_ctrl:1
	s_nop 1
	v_add_f32_dpp v31, v31, v31 row_mirror row_mask:0xf bank_mask:0xf bound_ctrl:1
	s_nop 1
	v_mov_b32_dpp v73, v31 row_bcast:15 row_mask:0xa bank_mask:0xf
	v_add_f32_e32 v31, v31, v73
	v_mov_b32_e32 v73, v1
	s_nop 1
	v_mov_b32_dpp v73, v31 row_bcast:31 row_mask:0xc bank_mask:0xf
	v_add_f32_e32 v31, v31, v73
	s_nop 0
	v_readlane_b32 s0, v31, 63
	s_nop 1
	v_add_f32_e32 v31, s0, v214
	v_cmp_gt_f32_e64 s[42:43], s65, v31
	v_mul_f32_e32 v73, 0x4b800000, v31
	s_nop 0
	v_cndmask_b32_e64 v31, v31, v73, s[42:43]
	v_rsq_f32_e32 v31, v31
	s_nop 0
	v_mul_f32_e32 v73, 0x45800000, v31
	v_cndmask_b32_e64 v31, v31, v73, s[42:43]
	v_mul_f32_e32 v74, 0x3db504f3, v31
	v_pk_mul_f32 v[26:27], v[26:27], v[74:75] op_sel_hi:[1,0]
	v_add_u32_e32 v74, 0x9000, v0
	v_cvt_pk_bf16_f32 v26, v26, v27
	v_add_u32_e32 v27, 0x8c00, v0
	ds_write2_b32 v27, v30, v26 offset0:128 offset1:196
	v_pk_mul_f32 v[30:31], v[12:13], v[36:37]
	v_lshlrev_b32_e32 v26, 16, v53
	v_pk_fma_f32 v[30:31], v[10:11], v[34:35], v[30:31]
	v_and_b32_e32 v27, 0xffff0000, v53
	v_pk_fma_f32 v[30:31], v[14:15], v[32:33], v[30:31]
	v_add_u32_e32 v75, 0x4c00, v0
	v_pk_fma_f32 v[30:31], v[16:17], v[26:27], v[30:31]
	s_nop 0
	v_mul_f32_e32 v34, 0xbfb8aa3b, v30
	v_mul_f32_e32 v35, 0xbfb8aa3b, v31
	v_exp_f32_e32 v34, v34
	v_exp_f32_e32 v35, v35
	v_add_f32_e32 v34, 1.0, v34
	v_add_f32_e32 v35, 1.0, v35
	v_rcp_f32_e32 v34, v34
	v_rcp_f32_e32 v35, v35
	s_nop 0
	v_pk_mul_f32 v[30:31], v[30:31], v[34:35]
	s_nop 0
	v_pk_mul_f32 v[34:35], v[30:31], v[30:31]
	s_nop 0
	v_add_f32_e32 v34, v34, v35
	v_mov_b32_e32 v35, v1
	s_nop 0
	v_add_f32_dpp v34, v34, v34 quad_perm:[1,0,3,2] row_mask:0xf bank_mask:0xf bound_ctrl:1
	s_nop 1
	v_add_f32_dpp v34, v34, v34 quad_perm:[2,3,0,1] row_mask:0xf bank_mask:0xf bound_ctrl:1
	s_nop 1
	v_add_f32_dpp v34, v34, v34 row_half_mirror row_mask:0xf bank_mask:0xf bound_ctrl:1
	s_nop 1
	v_add_f32_dpp v34, v34, v34 row_mirror row_mask:0xf bank_mask:0xf bound_ctrl:1
	s_nop 1
	v_mov_b32_dpp v35, v34 row_bcast:15 row_mask:0xa bank_mask:0xf
	v_add_f32_e32 v34, v34, v35
	v_mov_b32_e32 v35, v1
	s_nop 1
	v_mov_b32_dpp v35, v34 row_bcast:31 row_mask:0xc bank_mask:0xf
	v_add_f32_e32 v34, v34, v35
	s_nop 0
	v_readlane_b32 s0, v34, 63
	s_nop 1
	v_add_f32_e32 v34, s0, v214
	v_cmp_gt_f32_e64 s[42:43], s65, v34
	v_mul_f32_e32 v35, 0x4b800000, v34
	s_nop 0
	v_cndmask_b32_e64 v34, v34, v35, s[42:43]
	v_rsq_f32_e32 v34, v34
	s_nop 0
	v_mul_f32_e32 v35, 0x45800000, v34
	v_cndmask_b32_e64 v34, v34, v35, s[42:43]
	v_pk_mul_f32 v[30:31], v[30:31], v[34:35] op_sel_hi:[1,0]
	v_lshlrev_b32_e32 v34, 16, v43
	v_cvt_pk_bf16_f32 v30, v30, v31
	v_add_u32_e32 v31, 0x4800, v0
	ds_write2_b32 v31, v21, v30 offset0:128 offset1:196
	v_pk_mul_f32 v[30:31], v[8:9], v[22:23]
	v_and_b32_e32 v35, 0xffff0000, v43
	v_pk_fma_f32 v[24:25], v[2:3], v[24:25], v[30:31]
	s_nop 0
	v_pk_fma_f32 v[24:25], v[4:5], v[28:29], v[24:25]
	s_nop 0
	v_pk_fma_f32 v[24:25], v[6:7], v[34:35], v[24:25]
	s_nop 0
	v_mul_f32_e32 v21, 0xbfb8aa3b, v24
	v_exp_f32_e32 v21, v21
	s_nop 0
	v_add_f32_e32 v21, 1.0, v21
	v_rcp_f32_e32 v30, v21
	v_mul_f32_e32 v21, 0xbfb8aa3b, v25
	v_exp_f32_e32 v21, v21
	s_nop 0
	v_add_f32_e32 v21, 1.0, v21
	v_rcp_f32_e32 v31, v21
	s_nop 0
; #define LAS __attribute__((address_space(3)))
; __device__ __forceinline__ unsigned pk2(float lo, float hi) { return cvtpk(lo, hi); }
; __device__ __forceinline__ void phase_dn_prep(const KP kp, const int bid, const int G, int j, LAS unsigned char* lds, int tid0) {
;     ...
;           for (int t = 0; t < 8; ++t) { const float scq = rsqrtf(wave_sum(qa[t] * qa[t] + qb[t] * qb[t]) + 1e-6f) * 0.08838834764831845f, sck = rsqrtf(wave_sum(ka[t] * ka[t] + kb[t] * kb[t]) + 1e-6f);
;               *(LAS unsigned*)(Qb + (t0 + t) * 136 + 2 * lane) = pk2(qa[t] * scq, qb[t] * scq); *(LAS unsigned*)(Kb + (t0 + t) * 136 + 2 * lane) = pk2(ka[t] * sck, kb[t] * sck); } }
	v_pk_mul_f32 v[24:25], v[24:25], v[30:31]
	s_nop 0
	v_pk_mul_f32 v[30:31], v[24:25], v[24:25]
	s_nop 0
	v_add_f32_e32 v21, v30, v31
	v_mov_b32_e32 v30, v1
	s_nop 0
	v_add_f32_dpp v21, v21, v21 quad_perm:[1,0,3,2] row_mask:0xf bank_mask:0xf bound_ctrl:1
	s_nop 1
	v_add_f32_dpp v21, v21, v21 quad_perm:[2,3,0,1] row_mask:0xf bank_mask:0xf bound_ctrl:1
	s_nop 1
	v_add_f32_dpp v21, v21, v21 row_half_mirror row_mask:0xf bank_mask:0xf bound_ctrl:1
	s_nop 1
	v_add_f32_dpp v21, v21, v21 row_mirror row_mask:0xf bank_mask:0xf bound_ctrl:1
	s_nop 1
	v_mov_b32_dpp v30, v21 row_bcast:15 row_mask:0xa bank_mask:0xf
	v_add_f32_e32 v21, v21, v30
	v_mov_b32_e32 v30, v1
	s_nop 1
	v_mov_b32_dpp v30, v21 row_bcast:31 row_mask:0xc bank_mask:0xf
	v_add_f32_e32 v21, v21, v30
	s_nop 0
	v_readlane_b32 s0, v21, 63
	s_nop 1
	v_add_f32_e32 v21, s0, v214
	v_cmp_gt_f32_e64 s[42:43], s65, v21
	v_mul_f32_e32 v30, 0x4b800000, v21
	s_nop 0
	v_cndmask_b32_e64 v21, v21, v30, s[42:43]
	v_rsq_f32_e32 v21, v21
	s_nop 0
	v_mul_f32_e32 v30, 0x45800000, v21
	v_cndmask_b32_e64 v21, v21, v30, s[42:43]
	v_mul_f32_e32 v30, 0x3db504f3, v21
	v_pk_mul_f32 v[24:25], v[24:25], v[30:31] op_sel_hi:[1,0]
	v_lshlrev_b32_e32 v30, 16, v54
	v_cvt_pk_bf16_f32 v21, v24, v25
	v_pk_mul_f32 v[24:25], v[12:13], v[32:33]
	v_and_b32_e32 v31, 0xffff0000, v54
	v_pk_fma_f32 v[24:25], v[10:11], v[36:37], v[24:25]
	s_nop 0
	v_pk_fma_f32 v[24:25], v[14:15], v[26:27], v[24:25]
	s_nop 0
	v_pk_fma_f32 v[24:25], v[16:17], v[30:31], v[24:25]
	s_nop 0
	v_mul_f32_e32 v36, 0xbfb8aa3b, v24
	v_mul_f32_e32 v37, 0xbfb8aa3b, v25
	v_exp_f32_e32 v36, v36
	v_exp_f32_e32 v37, v37
	v_add_f32_e32 v36, 1.0, v36
	v_add_f32_e32 v37, 1.0, v37
	v_rcp_f32_e32 v36, v36
	v_rcp_f32_e32 v37, v37
	s_nop 0
	v_pk_mul_f32 v[24:25], v[24:25], v[36:37]
	s_nop 0
	v_pk_mul_f32 v[36:37], v[24:25], v[24:25]
	s_nop 0
	v_add_f32_e32 v36, v36, v37
	v_mov_b32_e32 v37, v1
	s_nop 0
	v_add_f32_dpp v36, v36, v36 quad_perm:[1,0,3,2] row_mask:0xf bank_mask:0xf bound_ctrl:1
	s_nop 1
	v_add_f32_dpp v36, v36, v36 quad_perm:[2,3,0,1] row_mask:0xf bank_mask:0xf bound_ctrl:1
	s_nop 1
	v_add_f32_dpp v36, v36, v36 row_half_mirror row_mask:0xf bank_mask:0xf bound_ctrl:1
	s_nop 1
	v_add_f32_dpp v36, v36, v36 row_mirror row_mask:0xf bank_mask:0xf bound_ctrl:1
	s_nop 1
	v_mov_b32_dpp v37, v36 row_bcast:15 row_mask:0xa bank_mask:0xf
	v_add_f32_e32 v36, v36, v37
	v_mov_b32_e32 v37, v1
	s_nop 1
	v_mov_b32_dpp v37, v36 row_bcast:31 row_mask:0xc bank_mask:0xf
	v_add_f32_e32 v36, v36, v37
	s_nop 0
	v_readlane_b32 s0, v36, 63
	s_nop 1
	v_add_f32_e32 v36, s0, v214
	v_cmp_gt_f32_e64 s[42:43], s65, v36
	v_mul_f32_e32 v37, 0x4b800000, v36
	s_nop 0
	v_cndmask_b32_e64 v36, v36, v37, s[42:43]
	v_rsq_f32_e32 v36, v36
	s_nop 0
	v_mul_f32_e32 v37, 0x45800000, v36
	v_cndmask_b32_e64 v36, v36, v37, s[42:43]
	v_pk_mul_f32 v[24:25], v[24:25], v[36:37] op_sel_hi:[1,0]
	v_pk_mul_f32 v[36:37], v[8:9], v[28:29]
	v_cvt_pk_bf16_f32 v73, v24, v25
	v_pk_fma_f32 v[22:23], v[2:3], v[22:23], v[36:37]
	v_lshlrev_b32_e32 v24, 16, v44
	v_and_b32_e32 v25, 0xffff0000, v44
	v_pk_fma_f32 v[22:23], v[4:5], v[34:35], v[22:23]
	s_nop 0
	v_pk_fma_f32 v[22:23], v[6:7], v[24:25], v[22:23]
	s_nop 0
	v_mul_f32_e32 v36, 0xbfb8aa3b, v22
	v_mul_f32_e32 v37, 0xbfb8aa3b, v23
	v_exp_f32_e32 v36, v36
	v_exp_f32_e32 v37, v37
	v_add_f32_e32 v36, 1.0, v36
	v_add_f32_e32 v37, 1.0, v37
	v_rcp_f32_e32 v36, v36
	v_rcp_f32_e32 v37, v37
	s_nop 0
	v_pk_mul_f32 v[22:23], v[22:23], v[36:37]
	s_nop 0
	v_pk_mul_f32 v[36:37], v[22:23], v[22:23]
	s_nop 0
	v_add_f32_e32 v36, v36, v37
	v_mov_b32_e32 v37, v1
	s_nop 0
	v_add_f32_dpp v36, v36, v36 quad_perm:[1,0,3,2] row_mask:0xf bank_mask:0xf bound_ctrl:1
	s_nop 1
	v_add_f32_dpp v36, v36, v36 quad_perm:[2,3,0,1] row_mask:0xf bank_mask:0xf bound_ctrl:1
	s_nop 1
	v_add_f32_dpp v36, v36, v36 row_half_mirror row_mask:0xf bank_mask:0xf bound_ctrl:1
	s_nop 1
	v_add_f32_dpp v36, v36, v36 row_mirror row_mask:0xf bank_mask:0xf bound_ctrl:1
	s_nop 1
	v_mov_b32_dpp v37, v36 row_bcast:15 row_mask:0xa bank_mask:0xf
	v_add_f32_e32 v36, v36, v37
	v_mov_b32_e32 v37, v1
	s_nop 1
	v_mov_b32_dpp v37, v36 row_bcast:31 row_mask:0xc bank_mask:0xf
	v_add_f32_e32 v36, v36, v37
	s_nop 0
	v_readlane_b32 s0, v36, 63
	s_nop 1
	v_add_f32_e32 v36, s0, v214
	v_cmp_gt_f32_e64 s[42:43], s65, v36
	v_mul_f32_e32 v37, 0x4b800000, v36
	s_nop 0
	v_cndmask_b32_e64 v36, v36, v37, s[42:43]
	v_rsq_f32_e32 v36, v36
	s_nop 0
	v_mul_f32_e32 v37, 0x45800000, v36
	v_cndmask_b32_e64 v36, v36, v37, s[42:43]
	v_mul_f32_e32 v36, 0x3db504f3, v36
	v_pk_mul_f32 v[22:23], v[22:23], v[36:37] op_sel_hi:[1,0]
	v_pk_mul_f32 v[36:37], v[12:13], v[26:27]
	v_cvt_pk_bf16_f32 v22, v22, v23
	v_pk_fma_f32 v[32:33], v[10:11], v[32:33], v[36:37]
	ds_write2_b32 v74, v21, v22 offset0:8 offset1:76
	v_lshlrev_b32_e32 v22, 16, v55
	v_and_b32_e32 v23, 0xffff0000, v55
	v_pk_fma_f32 v[32:33], v[14:15], v[30:31], v[32:33]
	s_nop 0
	v_pk_fma_f32 v[32:33], v[16:17], v[22:23], v[32:33]
	s_nop 0
	v_mul_f32_e32 v21, 0xbfb8aa3b, v32
	v_exp_f32_e32 v21, v21
	s_nop 0
	v_add_f32_e32 v21, 1.0, v21
	v_rcp_f32_e32 v36, v21
	v_mul_f32_e32 v21, 0xbfb8aa3b, v33
	v_exp_f32_e32 v21, v21
	s_nop 0
	v_add_f32_e32 v21, 1.0, v21
	v_rcp_f32_e32 v37, v21
	s_nop 0
	v_pk_mul_f32 v[32:33], v[32:33], v[36:37]
	s_nop 0
	v_pk_mul_f32 v[36:37], v[32:33], v[32:33]
	s_nop 0
	v_add_f32_e32 v21, v36, v37
	v_mov_b32_e32 v36, v1
	s_nop 0
	v_add_f32_dpp v21, v21, v21 quad_perm:[1,0,3,2] row_mask:0xf bank_mask:0xf bound_ctrl:1
	s_nop 1
	v_add_f32_dpp v21, v21, v21 quad_perm:[2,3,0,1] row_mask:0xf bank_mask:0xf bound_ctrl:1
	s_nop 1
	v_add_f32_dpp v21, v21, v21 row_half_mirror row_mask:0xf bank_mask:0xf bound_ctrl:1
; #define LAS __attribute__((address_space(3)))
; __device__ __forceinline__ unsigned pk2(float lo, float hi) { return cvtpk(lo, hi); }
; __device__ __forceinline__ float silu_(float x) { return x * __builtin_amdgcn_rcpf(1.f + __expf(-x)); }
; __device__ __forceinline__ void phase_dn_prep(const KP kp, const int bid, const int G, int j, LAS unsigned char* lds, int tid0) {
;     ...
;               for (int t = 0; t < 8; ++t) {
;                   const float ya = silu_(w0a * __uint_as_float(raw[t] << 16) + w1a * __uint_as_float(raw[t + 1] << 16) + w2a * __uint_as_float(raw[t + 2] << 16) + w3a * __uint_as_float(raw[t + 3] << 16));
;                   const float yb = silu_(w0b * __uint_as_float(raw[t] & 0xffff0000u) + w1b * __uint_as_float(raw[t + 1] & 0xffff0000u) + w2b * __uint_as_float(raw[t + 2] & 0xffff0000u) + w3b * __uint_as_float(raw[t + 3] & 0xffff0000u));
;                   if (part == 0) { qa[t] = ya; qb[t] = yb; } else if (part == 1) { ka[t] = ya; kb[t] = yb; } else { XL[(t0 + t) * 257 + 2 * lane] = ya; XL[(t0 + t) * 257 + 2 * lane + 1] = yb; } } }
; #pragma unroll
;           for (int t = 0; t < 8; ++t) { const float scq = rsqrtf(wave_sum(qa[t] * qa[t] + qb[t] * qb[t]) + 1e-6f) * 0.08838834764831845f, sck = rsqrtf(wave_sum(ka[t] * ka[t] + kb[t] * kb[t]) + 1e-6f);
;               *(LAS unsigned*)(Qb + (t0 + t) * 136 + 2 * lane) = pk2(qa[t] * scq, qb[t] * scq); *(LAS unsigned*)(Kb + (t0 + t) * 136 + 2 * lane) = pk2(ka[t] * sck, kb[t] * sck); } }
	s_nop 1
	v_add_f32_dpp v21, v21, v21 row_mirror row_mask:0xf bank_mask:0xf bound_ctrl:1
	s_nop 1
	v_mov_b32_dpp v36, v21 row_bcast:15 row_mask:0xa bank_mask:0xf
	v_add_f32_e32 v21, v21, v36
	v_mov_b32_e32 v36, v1
	s_nop 1
	v_mov_b32_dpp v36, v21 row_bcast:31 row_mask:0xc bank_mask:0xf
	v_add_f32_e32 v21, v21, v36
	s_nop 0
	v_readlane_b32 s0, v21, 63
	s_nop 1
	v_add_f32_e32 v21, s0, v214
	v_cmp_gt_f32_e64 s[42:43], s65, v21
	v_mul_f32_e32 v36, 0x4b800000, v21
	s_nop 0
	v_cndmask_b32_e64 v21, v21, v36, s[42:43]
	v_rsq_f32_e32 v21, v21
	s_nop 0
	v_mul_f32_e32 v36, 0x45800000, v21
	v_cndmask_b32_e64 v36, v21, v36, s[42:43]
	v_pk_mul_f32 v[32:33], v[32:33], v[36:37] op_sel_hi:[1,0]
	v_pk_mul_f32 v[36:37], v[8:9], v[34:35]
	v_cvt_pk_bf16_f32 v21, v32, v33
	v_pk_fma_f32 v[28:29], v[2:3], v[28:29], v[36:37]
	v_lshlrev_b32_e32 v32, 16, v45
	v_and_b32_e32 v33, 0xffff0000, v45
	v_pk_fma_f32 v[28:29], v[4:5], v[24:25], v[28:29]
	ds_write2_b32 v75, v73, v21 offset0:8 offset1:76
	v_pk_fma_f32 v[28:29], v[6:7], v[32:33], v[28:29]
	s_nop 0
	v_mul_f32_e32 v21, 0xbfb8aa3b, v28
	v_exp_f32_e32 v21, v21
	s_nop 0
	v_add_f32_e32 v21, 1.0, v21
	v_rcp_f32_e32 v36, v21
	v_mul_f32_e32 v21, 0xbfb8aa3b, v29
	v_exp_f32_e32 v21, v21
	s_nop 0
	v_add_f32_e32 v21, 1.0, v21
	v_rcp_f32_e32 v37, v21
	s_nop 0
	v_pk_mul_f32 v[28:29], v[28:29], v[36:37]
	s_nop 0
	v_pk_mul_f32 v[36:37], v[28:29], v[28:29]
	s_nop 0
	v_add_f32_e32 v21, v36, v37
	v_mov_b32_e32 v36, v1
	s_nop 0
	v_add_f32_dpp v21, v21, v21 quad_perm:[1,0,3,2] row_mask:0xf bank_mask:0xf bound_ctrl:1
	s_nop 1
	v_add_f32_dpp v21, v21, v21 quad_perm:[2,3,0,1] row_mask:0xf bank_mask:0xf bound_ctrl:1
	s_nop 1
	v_add_f32_dpp v21, v21, v21 row_half_mirror row_mask:0xf bank_mask:0xf bound_ctrl:1
	s_nop 1
	v_add_f32_dpp v21, v21, v21 row_mirror row_mask:0xf bank_mask:0xf bound_ctrl:1
	s_nop 1
	v_mov_b32_dpp v36, v21 row_bcast:15 row_mask:0xa bank_mask:0xf
	v_add_f32_e32 v21, v21, v36
	v_mov_b32_e32 v36, v1
	s_nop 1
	v_mov_b32_dpp v36, v21 row_bcast:31 row_mask:0xc bank_mask:0xf
	v_add_f32_e32 v21, v21, v36
	s_nop 0
	v_readlane_b32 s0, v21, 63
	s_nop 1
	v_add_f32_e32 v21, s0, v214
	v_cmp_gt_f32_e64 s[42:43], s65, v21
	v_mul_f32_e32 v36, 0x4b800000, v21
	s_nop 0
	v_cndmask_b32_e64 v21, v21, v36, s[42:43]
	v_rsq_f32_e32 v21, v21
	s_nop 0
	v_mul_f32_e32 v36, 0x45800000, v21
	v_cndmask_b32_e64 v21, v21, v36, s[42:43]
	v_mul_f32_e32 v36, 0x3db504f3, v21
	v_pk_mul_f32 v[28:29], v[28:29], v[36:37] op_sel_hi:[1,0]
	v_pk_mul_f32 v[36:37], v[12:13], v[30:31]
	v_cvt_pk_bf16_f32 v21, v28, v29
	v_pk_fma_f32 v[26:27], v[10:11], v[26:27], v[36:37]
	v_lshlrev_b32_e32 v28, 16, v56
	v_and_b32_e32 v29, 0xffff0000, v56
	v_pk_fma_f32 v[26:27], v[14:15], v[22:23], v[26:27]
	s_nop 0
	v_pk_fma_f32 v[26:27], v[16:17], v[28:29], v[26:27]
	s_nop 0
	v_mul_f32_e32 v36, 0xbfb8aa3b, v26
	v_mul_f32_e32 v37, 0xbfb8aa3b, v27
	v_exp_f32_e32 v36, v36
	v_exp_f32_e32 v37, v37
	v_add_f32_e32 v36, 1.0, v36
	v_add_f32_e32 v37, 1.0, v37
	v_rcp_f32_e32 v36, v36
	v_rcp_f32_e32 v37, v37
	s_nop 0
	v_pk_mul_f32 v[26:27], v[26:27], v[36:37]
	s_nop 0
	v_pk_mul_f32 v[36:37], v[26:27], v[26:27]
	s_nop 0
	v_add_f32_e32 v36, v36, v37
	v_mov_b32_e32 v37, v1
	s_nop 0
	v_add_f32_dpp v36, v36, v36 quad_perm:[1,0,3,2] row_mask:0xf bank_mask:0xf bound_ctrl:1
	s_nop 1
	v_add_f32_dpp v36, v36, v36 quad_perm:[2,3,0,1] row_mask:0xf bank_mask:0xf bound_ctrl:1
	s_nop 1
	v_add_f32_dpp v36, v36, v36 row_half_mirror row_mask:0xf bank_mask:0xf bound_ctrl:1
	s_nop 1
	v_add_f32_dpp v36, v36, v36 row_mirror row_mask:0xf bank_mask:0xf bound_ctrl:1
	s_nop 1
	v_mov_b32_dpp v37, v36 row_bcast:15 row_mask:0xa bank_mask:0xf
	v_add_f32_e32 v36, v36, v37
	v_mov_b32_e32 v37, v1
	s_nop 1
	v_mov_b32_dpp v37, v36 row_bcast:31 row_mask:0xc bank_mask:0xf
	v_add_f32_e32 v36, v36, v37
	s_nop 0
	v_readlane_b32 s0, v36, 63
	s_nop 1
	v_add_f32_e32 v36, s0, v214
	v_cmp_gt_f32_e64 s[42:43], s65, v36
	v_mul_f32_e32 v37, 0x4b800000, v36
	s_nop 0
	v_cndmask_b32_e64 v36, v36, v37, s[42:43]
	v_rsq_f32_e32 v36, v36
	s_nop 0
	v_mul_f32_e32 v37, 0x45800000, v36
	v_cndmask_b32_e64 v36, v36, v37, s[42:43]
	v_pk_mul_f32 v[26:27], v[26:27], v[36:37] op_sel_hi:[1,0]
	v_pk_mul_f32 v[36:37], v[8:9], v[24:25]
	v_cvt_pk_bf16_f32 v73, v26, v27
	v_pk_fma_f32 v[34:35], v[2:3], v[34:35], v[36:37]
	v_lshlrev_b32_e32 v26, 16, v46
	v_and_b32_e32 v27, 0xffff0000, v46
	v_pk_fma_f32 v[34:35], v[4:5], v[32:33], v[34:35]
	s_nop 0
	v_pk_fma_f32 v[34:35], v[6:7], v[26:27], v[34:35]
	s_nop 0
	v_mul_f32_e32 v36, 0xbfb8aa3b, v34
	v_mul_f32_e32 v37, 0xbfb8aa3b, v35
	v_exp_f32_e32 v36, v36
	v_exp_f32_e32 v37, v37
	v_add_f32_e32 v36, 1.0, v36
	v_add_f32_e32 v37, 1.0, v37
	v_rcp_f32_e32 v36, v36
	v_rcp_f32_e32 v37, v37
	s_nop 0
	v_pk_mul_f32 v[34:35], v[34:35], v[36:37]
	s_nop 0
	v_pk_mul_f32 v[36:37], v[34:35], v[34:35]
	s_nop 0
	v_add_f32_e32 v36, v36, v37
	v_mov_b32_e32 v37, v1
	s_nop 0
	v_add_f32_dpp v36, v36, v36 quad_perm:[1,0,3,2] row_mask:0xf bank_mask:0xf bound_ctrl:1
	s_nop 1
	v_add_f32_dpp v36, v36, v36 quad_perm:[2,3,0,1] row_mask:0xf bank_mask:0xf bound_ctrl:1
	s_nop 1
	v_add_f32_dpp v36, v36, v36 row_half_mirror row_mask:0xf bank_mask:0xf bound_ctrl:1
	s_nop 1
	v_add_f32_dpp v36, v36, v36 row_mirror row_mask:0xf bank_mask:0xf bound_ctrl:1
	s_nop 1
	v_mov_b32_dpp v37, v36 row_bcast:15 row_mask:0xa bank_mask:0xf
	v_add_f32_e32 v36, v36, v37
	v_mov_b32_e32 v37, v1
	s_nop 1
	v_mov_b32_dpp v37, v36 row_bcast:31 row_mask:0xc bank_mask:0xf
	v_add_f32_e32 v36, v36, v37
	s_nop 0
	v_readlane_b32 s0, v36, 63
	s_nop 1
	v_add_f32_e32 v36, s0, v214
	v_cmp_gt_f32_e64 s[42:43], s65, v36
	v_mul_f32_e32 v37, 0x4b800000, v36
	s_nop 0
; #define LAS __attribute__((address_space(3)))
; __device__ __forceinline__ unsigned pk2(float lo, float hi) { return cvtpk(lo, hi); }
; __device__ __forceinline__ float silu_(float x) { return x * __builtin_amdgcn_rcpf(1.f + __expf(-x)); }
; __device__ __forceinline__ void phase_dn_prep(const KP kp, const int bid, const int G, int j, LAS unsigned char* lds, int tid0) {
;     ...
;               for (int t = 0; t < 8; ++t) {
;                   const float ya = silu_(w0a * __uint_as_float(raw[t] << 16) + w1a * __uint_as_float(raw[t + 1] << 16) + w2a * __uint_as_float(raw[t + 2] << 16) + w3a * __uint_as_float(raw[t + 3] << 16));
;                   const float yb = silu_(w0b * __uint_as_float(raw[t] & 0xffff0000u) + w1b * __uint_as_float(raw[t + 1] & 0xffff0000u) + w2b * __uint_as_float(raw[t + 2] & 0xffff0000u) + w3b * __uint_as_float(raw[t + 3] & 0xffff0000u));
;                   if (part == 0) { qa[t] = ya; qb[t] = yb; } else if (part == 1) { ka[t] = ya; kb[t] = yb; } else { XL[(t0 + t) * 257 + 2 * lane] = ya; XL[(t0 + t) * 257 + 2 * lane + 1] = yb; } } }
; #pragma unroll
;           for (int t = 0; t < 8; ++t) { const float scq = rsqrtf(wave_sum(qa[t] * qa[t] + qb[t] * qb[t]) + 1e-6f) * 0.08838834764831845f, sck = rsqrtf(wave_sum(ka[t] * ka[t] + kb[t] * kb[t]) + 1e-6f);
;               *(LAS unsigned*)(Qb + (t0 + t) * 136 + 2 * lane) = pk2(qa[t] * scq, qb[t] * scq); *(LAS unsigned*)(Kb + (t0 + t) * 136 + 2 * lane) = pk2(ka[t] * sck, kb[t] * sck); } }
	v_cndmask_b32_e64 v36, v36, v37, s[42:43]
	v_rsq_f32_e32 v36, v36
	s_nop 0
	v_mul_f32_e32 v37, 0x45800000, v36
	v_cndmask_b32_e64 v36, v36, v37, s[42:43]
	v_mul_f32_e32 v36, 0x3db504f3, v36
	v_pk_mul_f32 v[34:35], v[34:35], v[36:37] op_sel_hi:[1,0]
	v_pk_mul_f32 v[36:37], v[12:13], v[22:23]
	v_cvt_pk_bf16_f32 v34, v34, v35
	v_pk_fma_f32 v[30:31], v[10:11], v[30:31], v[36:37]
	ds_write2_b32 v74, v21, v34 offset0:144 offset1:212
	v_lshlrev_b32_e32 v34, 16, v57
	v_and_b32_e32 v35, 0xffff0000, v57
	v_pk_fma_f32 v[30:31], v[14:15], v[28:29], v[30:31]
	s_nop 0
	v_pk_fma_f32 v[30:31], v[16:17], v[34:35], v[30:31]
	s_nop 0
	v_mul_f32_e32 v21, 0xbfb8aa3b, v30
	v_exp_f32_e32 v21, v21
	s_nop 0
	v_add_f32_e32 v21, 1.0, v21
	v_rcp_f32_e32 v36, v21
	v_mul_f32_e32 v21, 0xbfb8aa3b, v31
	v_exp_f32_e32 v21, v21
	s_nop 0
	v_add_f32_e32 v21, 1.0, v21
	v_rcp_f32_e32 v37, v21
	s_nop 0
	v_pk_mul_f32 v[30:31], v[30:31], v[36:37]
	s_nop 0
	v_pk_mul_f32 v[36:37], v[30:31], v[30:31]
	s_nop 0
	v_add_f32_e32 v21, v36, v37
	v_mov_b32_e32 v36, v1
	s_nop 0
	v_add_f32_dpp v21, v21, v21 quad_perm:[1,0,3,2] row_mask:0xf bank_mask:0xf bound_ctrl:1
	s_nop 1
	v_add_f32_dpp v21, v21, v21 quad_perm:[2,3,0,1] row_mask:0xf bank_mask:0xf bound_ctrl:1
	s_nop 1
	v_add_f32_dpp v21, v21, v21 row_half_mirror row_mask:0xf bank_mask:0xf bound_ctrl:1
	s_nop 1
	v_add_f32_dpp v21, v21, v21 row_mirror row_mask:0xf bank_mask:0xf bound_ctrl:1
	s_nop 1
	v_mov_b32_dpp v36, v21 row_bcast:15 row_mask:0xa bank_mask:0xf
	v_add_f32_e32 v21, v21, v36
	v_mov_b32_e32 v36, v1
	s_nop 1
	v_mov_b32_dpp v36, v21 row_bcast:31 row_mask:0xc bank_mask:0xf
	v_add_f32_e32 v21, v21, v36
	s_nop 0
	v_readlane_b32 s0, v21, 63
	s_nop 1
	v_add_f32_e32 v21, s0, v214
	v_cmp_gt_f32_e64 s[42:43], s65, v21
	v_mul_f32_e32 v36, 0x4b800000, v21
	s_nop 0
	v_cndmask_b32_e64 v21, v21, v36, s[42:43]
	v_rsq_f32_e32 v21, v21
	s_nop 0
	v_mul_f32_e32 v36, 0x45800000, v21
	v_cndmask_b32_e64 v36, v21, v36, s[42:43]
	v_pk_mul_f32 v[30:31], v[30:31], v[36:37] op_sel_hi:[1,0]
	v_pk_mul_f32 v[36:37], v[8:9], v[32:33]
	v_cvt_pk_bf16_f32 v21, v30, v31
	v_pk_fma_f32 v[24:25], v[2:3], v[24:25], v[36:37]
	v_lshlrev_b32_e32 v30, 16, v47
	v_and_b32_e32 v31, 0xffff0000, v47
	v_pk_fma_f32 v[24:25], v[4:5], v[26:27], v[24:25]
	ds_write2_b32 v75, v73, v21 offset0:144 offset1:212
	v_pk_fma_f32 v[24:25], v[6:7], v[30:31], v[24:25]
	v_pk_mul_f32 v[8:9], v[8:9], v[26:27]
	v_mul_f32_e32 v21, 0xbfb8aa3b, v24
	v_exp_f32_e32 v21, v21
	v_pk_fma_f32 v[2:3], v[2:3], v[32:33], v[8:9]
	v_add_f32_e32 v21, 1.0, v21
	v_rcp_f32_e32 v36, v21
	v_mul_f32_e32 v21, 0xbfb8aa3b, v25
	v_exp_f32_e32 v21, v21
	v_pk_fma_f32 v[2:3], v[4:5], v[30:31], v[2:3]
	v_add_f32_e32 v21, 1.0, v21
	v_rcp_f32_e32 v37, v21
	s_nop 0
	v_pk_mul_f32 v[24:25], v[24:25], v[36:37]
	s_nop 0
	v_pk_mul_f32 v[36:37], v[24:25], v[24:25]
	s_nop 0
	v_add_f32_e32 v21, v36, v37
	v_mov_b32_e32 v36, v1
	s_nop 0
	v_add_f32_dpp v21, v21, v21 quad_perm:[1,0,3,2] row_mask:0xf bank_mask:0xf bound_ctrl:1
	s_nop 1
	v_add_f32_dpp v21, v21, v21 quad_perm:[2,3,0,1] row_mask:0xf bank_mask:0xf bound_ctrl:1
	s_nop 1
	v_add_f32_dpp v21, v21, v21 row_half_mirror row_mask:0xf bank_mask:0xf bound_ctrl:1
	s_nop 1
	v_add_f32_dpp v21, v21, v21 row_mirror row_mask:0xf bank_mask:0xf bound_ctrl:1
	s_nop 1
	v_mov_b32_dpp v36, v21 row_bcast:15 row_mask:0xa bank_mask:0xf
	v_add_f32_e32 v21, v21, v36
	v_mov_b32_e32 v36, v1
	s_nop 1
	v_mov_b32_dpp v36, v21 row_bcast:31 row_mask:0xc bank_mask:0xf
	v_add_f32_e32 v21, v21, v36
	s_nop 0
	v_readlane_b32 s0, v21, 63
	s_nop 1
	v_add_f32_e32 v21, s0, v214
	v_cmp_gt_f32_e64 s[42:43], s65, v21
	v_mul_f32_e32 v36, 0x4b800000, v21
	s_nop 0
	v_cndmask_b32_e64 v21, v21, v36, s[42:43]
	v_rsq_f32_e32 v21, v21
	s_nop 0
	v_mul_f32_e32 v36, 0x45800000, v21
	v_cndmask_b32_e64 v21, v21, v36, s[42:43]
	v_mul_f32_e32 v36, 0x3db504f3, v21
	v_pk_mul_f32 v[24:25], v[24:25], v[36:37] op_sel_hi:[1,0]
	v_pk_mul_f32 v[36:37], v[12:13], v[28:29]
	v_cvt_pk_bf16_f32 v21, v24, v25
	v_pk_fma_f32 v[22:23], v[10:11], v[22:23], v[36:37]
	v_lshlrev_b32_e32 v24, 16, v58
	v_and_b32_e32 v25, 0xffff0000, v58
	v_pk_fma_f32 v[22:23], v[14:15], v[34:35], v[22:23]
	s_nop 0
	v_pk_fma_f32 v[22:23], v[16:17], v[24:25], v[22:23]
	s_nop 0
	v_mul_f32_e32 v36, 0xbfb8aa3b, v22
	v_mul_f32_e32 v37, 0xbfb8aa3b, v23
	v_exp_f32_e32 v36, v36
	v_exp_f32_e32 v37, v37
	v_add_f32_e32 v36, 1.0, v36
	v_add_f32_e32 v37, 1.0, v37
	v_rcp_f32_e32 v36, v36
	v_rcp_f32_e32 v37, v37
	s_nop 0
	v_pk_mul_f32 v[22:23], v[22:23], v[36:37]
	s_nop 0
	v_pk_mul_f32 v[36:37], v[22:23], v[22:23]
	s_nop 0
	v_add_f32_e32 v36, v36, v37
	v_mov_b32_e32 v37, v1
	s_nop 0
	v_add_f32_dpp v36, v36, v36 quad_perm:[1,0,3,2] row_mask:0xf bank_mask:0xf bound_ctrl:1
	s_nop 1
	v_add_f32_dpp v36, v36, v36 quad_perm:[2,3,0,1] row_mask:0xf bank_mask:0xf bound_ctrl:1
	s_nop 1
	v_add_f32_dpp v36, v36, v36 row_half_mirror row_mask:0xf bank_mask:0xf bound_ctrl:1
	s_nop 1
	v_add_f32_dpp v36, v36, v36 row_mirror row_mask:0xf bank_mask:0xf bound_ctrl:1
	s_nop 1
	v_mov_b32_dpp v37, v36 row_bcast:15 row_mask:0xa bank_mask:0xf
	v_add_f32_e32 v36, v36, v37
	v_mov_b32_e32 v37, v1
	s_nop 1
	v_mov_b32_dpp v37, v36 row_bcast:31 row_mask:0xc bank_mask:0xf
	v_add_f32_e32 v36, v36, v37
	s_nop 0
	v_readlane_b32 s0, v36, 63
	s_nop 1
; #define LAS __attribute__((address_space(3)))
; __device__ __forceinline__ float bf2f(bf16 b) { return __uint_as_float(((unsigned)b) << 16); }
; __device__ __forceinline__ unsigned pk2(float lo, float hi) { return cvtpk(lo, hi); }
; __device__ __forceinline__ float sigmoid_(float x) { return __builtin_amdgcn_rcpf(1.f + __expf(-x)); }
; __device__ __forceinline__ float softplus_(float x) { return x > 15.f ? x : (x < -15.f ? __expf(x) : __logf(1.f + __expf(x))); }
; __device__ __forceinline__ void phase_dn_prep(const KP kp, const int bid, const int G, int j, LAS unsigned char* lds, int tid0) {
;     ...
;           for (int t = 0; t < 8; ++t) { const float scq = rsqrtf(wave_sum(qa[t] * qa[t] + qb[t] * qb[t]) + 1e-6f) * 0.08838834764831845f, sck = rsqrtf(wave_sum(ka[t] * ka[t] + kb[t] * kb[t]) + 1e-6f);
;               *(LAS unsigned*)(Qb + (t0 + t) * 136 + 2 * lane) = pk2(qa[t] * scq, qb[t] * scq); *(LAS unsigned*)(Kb + (t0 + t) * 136 + 2 * lane) = pk2(ka[t] * sck, kb[t] * sck); } }
;         if (wave == 0) { const size_t ro = (size_t)(row0 + lane) * NAB;
;             float gv = -__expf(kp.in(15)[j * 8 + h]) * softplus_(bf2f(U[ro + 7176 + h]) + kp.in(16)[j * 8 + h]);
; #pragma unroll
;             for (int o = 1; o < 64; o <<= 1) { const float tt = __shfl_up(gv, o); if (lane >= o) gv += tt; }
;             GLs[lane] = gv; BLs[lane] = sigmoid_(bf2f(U[ro + 7168 + h])); }
	v_add_f32_e32 v36, s0, v214
	v_cmp_gt_f32_e64 s[42:43], s65, v36
	v_mul_f32_e32 v37, 0x4b800000, v36
	s_nop 0
	v_cndmask_b32_e64 v36, v36, v37, s[42:43]
	v_rsq_f32_e32 v36, v36
	s_nop 0
	v_mul_f32_e32 v37, 0x45800000, v36
	v_cndmask_b32_e64 v36, v36, v37, s[42:43]
	v_pk_mul_f32 v[22:23], v[22:23], v[36:37] op_sel_hi:[1,0]
	s_nop 0
	v_cvt_pk_bf16_f32 v36, v22, v23
	v_lshlrev_b32_e32 v22, 16, v48
	v_and_b32_e32 v23, 0xffff0000, v48
	v_pk_fma_f32 v[2:3], v[6:7], v[22:23], v[2:3]
	s_nop 0
	v_mul_f32_e32 v4, 0xbfb8aa3b, v2
	v_mul_f32_e32 v5, 0xbfb8aa3b, v3
	v_exp_f32_e32 v4, v4
	v_exp_f32_e32 v5, v5
	v_add_f32_e32 v4, 1.0, v4
	v_add_f32_e32 v5, 1.0, v5
	v_rcp_f32_e32 v4, v4
	v_rcp_f32_e32 v5, v5
	s_nop 0
	v_pk_mul_f32 v[2:3], v[2:3], v[4:5]
	s_nop 0
	v_pk_mul_f32 v[4:5], v[2:3], v[2:3]
	s_nop 0
	v_add_f32_e32 v4, v4, v5
	v_mov_b32_e32 v5, v1
	s_nop 0
	v_add_f32_dpp v4, v4, v4 quad_perm:[1,0,3,2] row_mask:0xf bank_mask:0xf bound_ctrl:1
	s_nop 1
	v_add_f32_dpp v4, v4, v4 quad_perm:[2,3,0,1] row_mask:0xf bank_mask:0xf bound_ctrl:1
	s_nop 1
	v_add_f32_dpp v4, v4, v4 row_half_mirror row_mask:0xf bank_mask:0xf bound_ctrl:1
	s_nop 1
	v_add_f32_dpp v4, v4, v4 row_mirror row_mask:0xf bank_mask:0xf bound_ctrl:1
	s_nop 1
	v_mov_b32_dpp v5, v4 row_bcast:15 row_mask:0xa bank_mask:0xf
	v_add_f32_e32 v4, v4, v5
	v_mov_b32_e32 v5, v1
	s_nop 1
	v_mov_b32_dpp v5, v4 row_bcast:31 row_mask:0xc bank_mask:0xf
	v_add_f32_e32 v4, v4, v5
	s_nop 0
	v_readlane_b32 s0, v4, 63
	s_nop 1
	v_add_f32_e32 v4, s0, v214
	v_cmp_gt_f32_e64 s[42:43], s65, v4
	v_mul_f32_e32 v5, 0x4b800000, v4
	s_nop 0
	v_cndmask_b32_e64 v4, v4, v5, s[42:43]
	v_rsq_f32_e32 v4, v4
	s_nop 0
	v_mul_f32_e32 v5, 0x45800000, v4
	v_cndmask_b32_e64 v4, v4, v5, s[42:43]
	v_mul_f32_e32 v4, 0x3db504f3, v4
	v_pk_mul_f32 v[2:3], v[2:3], v[4:5] op_sel_hi:[1,0]
	v_pk_mul_f32 v[4:5], v[12:13], v[34:35]
	v_cvt_pk_bf16_f32 v2, v2, v3
	v_add_u32_e32 v3, 0x9400, v0
	v_pk_fma_f32 v[4:5], v[10:11], v[28:29], v[4:5]
	ds_write2_b32 v3, v21, v2 offset0:24 offset1:92
	v_lshlrev_b32_e32 v2, 16, v59
	v_and_b32_e32 v3, 0xffff0000, v59
	v_pk_fma_f32 v[4:5], v[14:15], v[24:25], v[4:5]
	v_add_u32_e32 v0, 0x5000, v0
	v_pk_fma_f32 v[2:3], v[16:17], v[2:3], v[4:5]
	s_nop 0
	v_mul_f32_e32 v4, 0xbfb8aa3b, v2
	v_mul_f32_e32 v5, 0xbfb8aa3b, v3
	v_exp_f32_e32 v4, v4
	v_exp_f32_e32 v5, v5
	v_add_f32_e32 v4, 1.0, v4
	v_add_f32_e32 v5, 1.0, v5
	v_rcp_f32_e32 v4, v4
	v_rcp_f32_e32 v5, v5
	s_nop 0
	v_pk_mul_f32 v[2:3], v[2:3], v[4:5]
	s_nop 0
	v_pk_mul_f32 v[4:5], v[2:3], v[2:3]
	s_nop 0
	v_add_f32_e32 v4, v4, v5
	v_mov_b32_e32 v5, v1
	s_nop 0
	v_add_f32_dpp v4, v4, v4 quad_perm:[1,0,3,2] row_mask:0xf bank_mask:0xf bound_ctrl:1
	s_nop 1
	v_add_f32_dpp v4, v4, v4 quad_perm:[2,3,0,1] row_mask:0xf bank_mask:0xf bound_ctrl:1
	s_nop 1
	v_add_f32_dpp v4, v4, v4 row_half_mirror row_mask:0xf bank_mask:0xf bound_ctrl:1
	s_nop 1
	v_add_f32_dpp v4, v4, v4 row_mirror row_mask:0xf bank_mask:0xf bound_ctrl:1
	s_nop 1
	v_mov_b32_dpp v5, v4 row_bcast:15 row_mask:0xa bank_mask:0xf
	v_add_f32_e32 v4, v4, v5
	v_mov_b32_e32 v5, v1
	s_nop 1
	v_mov_b32_dpp v5, v4 row_bcast:31 row_mask:0xc bank_mask:0xf
	v_add_f32_e32 v4, v4, v5
	s_nop 0
	v_readlane_b32 s0, v4, 63
	s_nop 1
	v_add_f32_e32 v4, s0, v214
	v_cmp_gt_f32_e64 s[42:43], s65, v4
	v_mul_f32_e32 v5, 0x4b800000, v4
	s_nop 0
	v_cndmask_b32_e64 v4, v4, v5, s[42:43]
	v_rsq_f32_e32 v4, v4
	s_nop 0
	v_mul_f32_e32 v5, 0x45800000, v4
	v_cndmask_b32_e64 v4, v4, v5, s[42:43]
	v_pk_mul_f32 v[2:3], v[2:3], v[4:5] op_sel_hi:[1,0]
	s_nop 0
	v_cvt_pk_bf16_f32 v2, v2, v3
	ds_write2_b32 v0, v36, v2 offset0:24 offset1:92
	s_and_saveexec_b64 s[0:1], vcc
	s_cbranch_execz .LBB0_560
	s_load_dwordx4 s[16:19], s[60:61], 0x78
	s_lshl_b32 s3, s3, 6
	s_and_b32 s4, s59, 0xfffff800
	s_or_b32 s3, s3, s4
	s_or_b32 s4, s2, s6
	s_ashr_i32 s5, s4, 31
	s_lshl_b64 s[4:5], s[4:5], 2
	s_waitcnt lgkmcnt(0)
	s_add_u32 s10, s16, s4
	v_or_b32_e32 v4, s3, v20
	s_addc_u32 s11, s17, s5
	v_mov_b64_e32 v[2:3], s[62:63]
	s_movk_i32 s3, 0x3a00
	global_load_dword v0, v1, s[10:11]
	v_mad_i64_i32 v[2:3], s[10:11], v4, s3, v[2:3]
	s_lshl_b32 s38, s2, 1
	v_lshl_add_u64 v[2:3], v[2:3], 0, s[38:39]
	s_movk_i32 s2, 0x3000
	v_add_co_u32_e32 v4, vcc, s2, v2
	s_add_u32 s2, s18, s4
	s_nop 0
	v_addc_co_u32_e32 v5, vcc, 0, v3, vcc
	global_load_ushort v4, v[4:5], off offset:2064
	global_load_ushort v7, v[4:5], off offset:2048
	s_addc_u32 s3, s19, s5
	global_load_dword v5, v1, s[2:3]
	s_waitcnt vmcnt(1)
	v_lshlrev_b32_e32 v4, 16, v4
	s_waitcnt vmcnt(0)
	v_add_f32_e32 v4, v5, v4
	v_cmp_nlt_f32_e32 vcc, s67, v4
	s_and_saveexec_b64 s[2:3], vcc
	s_cbranch_execz .LBB0_559
	v_cmp_ngt_f32_e32 vcc, s68, v4
	v_mul_f32_e32 v4, 0x3fb8aa3b, v4
	v_exp_f32_e32 v4, v4
	s_and_saveexec_b64 s[4:5], vcc
	s_cbranch_execz .LBB0_558
	v_add_f32_e32 v4, 1.0, v4
	v_cmp_gt_f32_e32 vcc, s65, v4
	s_mov_b32 s9, 0x3f317217
	s_nop 0
	v_cndmask_b32_e64 v5, 0, 32, vcc
	v_ldexp_f32 v4, v4, v5
	v_log_f32_e32 v4, v4
	s_nop 0
	v_mul_f32_e32 v5, 0x3f317217, v4
	v_fma_f32 v5, v4, s9, -v5
	v_fmac_f32_e32 v5, 0x3377d1cf, v4
	s_mov_b32 s9, 0x7f800000
	v_fmac_f32_e32 v5, 0x3f317217, v4
	v_cmp_lt_f32_e64 s[42:43], |v4|, s9
	s_nop 1
	v_cndmask_b32_e64 v4, v4, v5, s[42:43]
	v_cndmask_b32_e32 v5, 0, v217, vcc
	v_sub_f32_e32 v4, v4, v5

; __device__ __forceinline__ float bf2f(bf16 b) { return __uint_as_float(((unsigned)b) << 16); }
; __device__ __forceinline__ float sigmoid_(float x) { return __builtin_amdgcn_rcpf(1.f + __expf(-x)); }
; __device__ __forceinline__ float softplus_(float x) { return x > 15.f ? x : (x < -15.f ? __expf(x) : __logf(1.f + __expf(x))); }
; __device__ __forceinline__ void phase_dn_prep(const KP kp, const int bid, const int G, int j, LAS unsigned char* lds, int tid0) {
;     ...
;         if (wave == 0) { const size_t ro = (size_t)(row0 + lane) * NAB;
;             float gv = -__expf(kp.in(15)[j * 8 + h]) * softplus_(bf2f(U[ro + 7176 + h]) + kp.in(16)[j * 8 + h]);
; #pragma unroll
;             for (int o = 1; o < 64; o <<= 1) { const float tt = __shfl_up(gv, o); if (lane >= o) gv += tt; }
;             GLs[lane] = gv; BLs[lane] = sigmoid_(bf2f(U[ro + 7168 + h])); }
.LBB0_559:
	s_or_b64 exec, exec, s[2:3]
	v_add_co_u32_e32 v2, vcc, 0x3000, v2
	v_mul_f32_e32 v0, 0x3fb8aa3b, v0
	s_nop 0
	v_addc_co_u32_e32 v3, vcc, 0, v3, vcc
	v_exp_f32_e32 v0, v0
	v_and_b32_e32 v5, 64, v216
	v_add_u32_e32 v6, -1, v216
	v_cmp_lt_i32_e32 vcc, v6, v5
	v_mul_f32_e64 v3, v4, -v0
	s_waitcnt vmcnt(0)
	v_lshlrev_b32_e32 v2, 16, v7
	v_cndmask_b32_e32 v6, v6, v216, vcc
	v_lshlrev_b32_e32 v6, 2, v6
	ds_bpermute_b32 v6, v6, v3
	v_cmp_eq_u32_e32 vcc, 0, v68
	v_mul_f32_e32 v2, 0xbfb8aa3b, v2
	v_exp_f32_e32 v2, v2
	s_waitcnt lgkmcnt(0)
	v_fma_f32 v0, v4, -v0, v6
	v_cndmask_b32_e32 v0, v0, v3, vcc
	v_add_u32_e32 v3, -2, v216
	v_cmp_lt_i32_e32 vcc, v3, v5
	v_add_f32_e32 v2, 1.0, v2
	v_rcp_f32_e32 v2, v2
	v_cndmask_b32_e32 v3, v3, v216, vcc
	v_lshlrev_b32_e32 v3, 2, v3
	ds_bpermute_b32 v3, v3, v0
	v_cmp_gt_u32_e32 vcc, 2, v68
	s_waitcnt lgkmcnt(0)
	v_add_f32_e32 v3, v0, v3
	v_cndmask_b32_e32 v0, v3, v0, vcc
	v_add_u32_e32 v3, -4, v216
	v_cmp_lt_i32_e32 vcc, v3, v5
	s_nop 1
	v_cndmask_b32_e32 v3, v3, v216, vcc
	v_lshlrev_b32_e32 v3, 2, v3
	ds_bpermute_b32 v3, v3, v0
	v_cmp_gt_u32_e32 vcc, 4, v68
	s_waitcnt lgkmcnt(0)
	v_add_f32_e32 v3, v0, v3
	v_cndmask_b32_e32 v0, v3, v0, vcc
	v_add_u32_e32 v3, -8, v216
	v_cmp_lt_i32_e32 vcc, v3, v5
	s_nop 1
	v_cndmask_b32_e32 v3, v3, v216, vcc
	v_lshlrev_b32_e32 v3, 2, v3
	ds_bpermute_b32 v3, v3, v0
	v_cmp_gt_u32_e32 vcc, 8, v68
	s_waitcnt lgkmcnt(0)
	v_add_f32_e32 v3, v0, v3
	v_cndmask_b32_e32 v0, v3, v0, vcc
	v_add_u32_e32 v3, -16, v216
	v_cmp_lt_i32_e32 vcc, v3, v5
	s_nop 1
	v_cndmask_b32_e32 v3, v3, v216, vcc
	v_lshlrev_b32_e32 v3, 2, v3
	ds_bpermute_b32 v3, v3, v0
	v_cmp_gt_u32_e32 vcc, 16, v68
	s_waitcnt lgkmcnt(0)
	v_add_f32_e32 v3, v0, v3
	v_cndmask_b32_e32 v0, v3, v0, vcc
	v_subrev_u32_e32 v3, 32, v216
	v_cmp_lt_i32_e32 vcc, v3, v5
	s_nop 1
	v_cndmask_b32_e32 v3, v3, v216, vcc
	v_lshlrev_b32_e32 v3, 2, v3
	ds_bpermute_b32 v3, v3, v0
	v_cmp_gt_u32_e32 vcc, 32, v68
	s_waitcnt lgkmcnt(0)
	v_add_f32_e32 v3, v0, v3
	v_cndmask_b32_e32 v0, v3, v0, vcc
	v_lshl_add_u32 v3, v68, 2, 0
	ds_write2st64_b32 v3, v0, v2 offset0:68 offset1:69
